# panel-ready wait: the acquire cache invalidate after the poll dropped (the grid barrier at phase start already invalidated; a panel is never read before it is ready)
# baseline (speedup 1.0000x reference)
.LBB0_213:
	s_waitcnt vmcnt(0) lgkmcnt(0)
	s_waitcnt vmcnt(0)
